# P3-end and P7-end barriers made XCD-local (no L2 write-back / cross-XCD hop) when a run-time check shows each 4-workgroup row group shares one XCC; consumers only read their own row group
# speedup vs baseline: 1.0051x; 1.0050x over previous
; #define LAS __attribute__((address_space(3)))
; DI unsigned xb_add(unsigned* p, unsigned v) { return __hip_atomic_fetch_add(p, v, __ATOMIC_RELAXED, __HIP_MEMORY_SCOPE_AGENT); }
; DI unsigned xb_xcc_id() { return (unsigned)__builtin_amdgcn_s_getreg((3 << 11) | 20) & 0xFu; }
; DI XcdBarrier xcd_barrier_post(unsigned* bar, volatile LAS unsigned* st) {
;   XcdBarrier b; b.bar = bar; b.x = xb_xcc_id(); b.st = st;
;   if (threadIdx.x == 0) (void)xb_add(&bar[XB_XCNT(b.x)], 1u);
.LBB0_3:
	s_or_b64 exec, exec, s[0:1]
	s_mov_b32 s0, 25
	s_waitcnt lgkmcnt(0)
	s_barrier
	s_ashr_i32 s1, s0, 31
	s_lshl_b64 s[0:1], s[0:1], 3
	s_add_u32 s0, s70, s0
	s_addc_u32 s1, s71, s1
	s_load_dwordx2 s[2:3], s[0:1], 0x0
	s_getreg_b32 s0, hwreg(HW_REG_XCC_ID, 0, 4)
	s_mov_b32 s4, 25
	s_mov_b32 s6, 0
	v_cmp_eq_u32_e64 s[8:9], 0, v224
	s_waitcnt lgkmcnt(0)
	s_add_u32 s10, s2, 0xf8e2000
	s_addc_u32 s11, s3, 0
	s_and_b32 s40, s0, 15
	v_writelane_b32 v255, s40, 59
	s_mov_b32 s100, 2
	s_nop 0
	v_writelane_b32 v255, s100, 56
	s_mov_b64 s[0:1], exec
	v_writelane_b32 v252, s8, 3
	s_nop 1
	v_writelane_b32 v252, s9, 4
	s_and_b64 s[8:9], s[0:1], s[8:9]
	s_mov_b64 exec, s[8:9]
	s_cbranch_execz .LBB0_6
	s_mov_b64 s[8:9], exec
	v_mbcnt_lo_u32_b32 v0, s8, 0
	v_mbcnt_hi_u32_b32 v0, s9, v0
	v_cmp_eq_u32_e32 vcc, 0, v0
	s_and_b64 s[12:13], exec, vcc
	s_mov_b64 exec, s[12:13]
	s_cbranch_execz .LBB0_6
	s_lshl_b32 s5, s40, 8
	s_bcnt1_i32_b64 s7, s[8:9]
	v_mov_b32_e32 v0, s5
	v_mov_b32_e32 v1, s7
	global_atomic_add v0, v1, s[10:11] offset:1024
	v_readlane_b32 s100, v252, 0
	s_lshl_b32 s101, s40, 2
	s_and_b32 s100, s100, 63
	s_lshl_b32 s101, 1, s101
	s_lshl_b32 s100, s100, 2
	s_cmp_gt_u32 s40, 7
	s_cselect_b32 s101, 0, s101
	v_mov_b32_e32 v0, s100
	v_mov_b32_e32 v1, s101
	s_nop 0
	global_atomic_add v0, v1, s[10:11]

; #define LAS __attribute__((address_space(3)))
; DI unsigned xb_add(unsigned* p, unsigned v) { return __hip_atomic_fetch_add(p, v, __ATOMIC_RELAXED, __HIP_MEMORY_SCOPE_AGENT); }
; DI unsigned xb_xcc_id() { return (unsigned)__builtin_amdgcn_s_getreg((3 << 11) | 20) & 0xFu; }
; DI XcdBarrier xcd_barrier_post(unsigned* bar, volatile LAS unsigned* st) {
;   XcdBarrier b; b.bar = bar; b.x = xb_xcc_id(); b.st = st;
;   if (threadIdx.x == 0) (void)xb_add(&bar[XB_XCNT(b.x)], 1u);
; DI void convert_mat(const float* W, int K, int N, const float* g, bf16_t* Wt, int mode, int& off, int vb, int nb, bool f16 = false) {
;   const int ntn = (N + 127) >> 7;
;   const int ntiles = (K >> 6) * ntn;
;   const int first = (int)((vb + nb - (off % nb)) % nb);
;   for (int i = first; i < ntiles; i += nb) convert_tile(W, K, N, g, Wt, mode, i / ntn, i % ntn, f16);
;   off += ntiles;
; }
.LBB0_181:
	s_or_b64 exec, exec, s[0:1]
	s_load_dwordx2 s[0:1], s[70:71], 0xc8
	v_readlane_b32 s100, v252, 0
	v_readlane_b32 s101, v255, 59
	s_and_b32 s100, s100, 63
	s_lshl_b32 s100, s100, 2
	v_mov_b32_e32 v0, s100
	s_waitcnt lgkmcnt(0)
	s_add_u32 s0, s0, 0xf8e2000
	s_addc_u32 s1, s1, 0
	global_load_dword v1, v0, s[0:1] sc1
	s_lshl_b32 s100, s101, 2
	s_lshl_b32 s100, 4, s100
	s_cmp_gt_u32 s101, 7
	s_cselect_b32 s100, -1, s100
	s_waitcnt vmcnt(0)
	v_readfirstlane_b32 s101, v1
	s_nop 0
	s_cmp_eq_u32 s101, s100
	s_cbranch_scc1 .Lxl_ok
	v_mov_b32_e32 v0, 0x100
	v_mov_b32_e32 v1, 1
	global_atomic_add v0, v1, s[0:1]
.Lxl_ok:
	s_load_dwordx2 s[6:7], s[70:71], 0xd0
	s_waitcnt lgkmcnt(0)
	v_readlane_b32 s7, v252, 0
	v_mov_b32_e32 v2, 0
	v_mov_b32_e32 v234, 0x21010
	v_mbcnt_hi_u32_b32 v225, -1, v21
	s_cmpk_lt_i32 s6, 0x100
	s_cselect_b64 s[0:1], -1, 0
	v_writelane_b32 v253, s0, 27
	s_cmpk_gt_i32 s7, 0x7f
	v_mov_b32_e32 v235, 0xf149f2ca
	v_writelane_b32 v253, s1, 28
	s_cselect_b64 s[0:1], -1, 0
	v_writelane_b32 v253, s0, 29
	s_add_i32 s4, s6, 0xffffff80
	s_lshl_b32 s8, s4, 9
	v_writelane_b32 v253, s1, 30
	s_add_i32 s1, s7, 0xffffff80
	s_add_i32 s0, s4, s1
	s_lshl_b32 s1, s1, 9
	v_writelane_b32 v253, s1, 31
	v_readlane_b32 s1, v252, 12
	s_cmpk_lt_i32 s1, 0x100
	v_cvt_f32_u32_e32 v0, s4
	s_cselect_b64 s[2:3], -1, 0
	s_lshl_b32 s10, s6, 9
	v_writelane_b32 v253, s2, 32
	s_cmpk_lt_i32 s7, 0x2c0
	v_rcp_iflag_f32_e32 v0, v0
	v_writelane_b32 v253, s3, 33
	s_cselect_b64 s[2:3], -1, 0
	v_writelane_b32 v253, s2, 34
	s_cmpk_lt_i32 s7, 0x200
	v_mul_f32_e32 v0, 0x4f7ffffe, v0
	v_writelane_b32 v253, s3, 35
	s_cselect_b64 s[2:3], -1, 0
	v_writelane_b32 v253, s2, 36
	s_cmpk_lt_i32 s7, 0x100
	v_cvt_u32_f32_e32 v0, v0
	v_writelane_b32 v253, s3, 37
	s_cselect_b64 s[2:3], -1, 0
	v_writelane_b32 v253, s2, 38
	s_cmpk_lt_i32 s7, 0xa0
	s_mov_b32 s17, 0xefa18f08
	v_writelane_b32 v253, s3, 39
	s_cselect_b64 s[2:3], -1, 0
	v_writelane_b32 v253, s2, 40
	s_cmpk_lt_i32 s7, 0x600
	s_mov_b64 s[34:35], 0x40080
	v_writelane_b32 v253, s3, 41
	s_cselect_b64 s[2:3], -1, 0
	v_writelane_b32 v253, s2, 42
	s_sub_i32 s1, 0x80, s6
	s_mov_b64 s[18:19], 0x40100
	v_writelane_b32 v253, s3, 43
	v_readfirstlane_b32 s2, v0
	s_mul_i32 s3, s1, s2
	s_mul_hi_u32 s3, s2, s3
	s_add_i32 s2, s2, s3
	s_mul_hi_u32 s2, s0, s2
	s_mul_i32 s2, s2, s4
	s_sub_i32 s2, s0, s2
	s_sub_i32 s3, s2, s4
	s_cmp_ge_u32 s2, s4
	s_cselect_b32 s2, s3, s2
	s_sub_i32 s3, s2, s4
	s_cmp_ge_u32 s2, s4
	s_cselect_b32 s2, s3, s2
	s_cmpk_lt_u32 s2, 0x100
	v_writelane_b32 v253, s2, 44
	s_cselect_b64 s[2:3], -1, 0
	s_max_i32 s1, s4, s1
	v_cvt_f32_u32_e32 v0, s1
	v_writelane_b32 v253, s2, 45
	s_mov_b64 s[22:23], 0x180
	s_mov_b32 s28, 0x3e16c740
	v_rcp_iflag_f32_e32 v0, v0
	v_writelane_b32 v253, s3, 46
	s_sub_i32 s2, 0, s1
	v_writelane_b32 v253, s4, 47
	v_mul_f32_e32 v0, 0x4f7ffffe, v0
	v_cvt_u32_f32_e32 v0, v0
	s_mov_b32 s16, 0x3e38aa3b
	s_mov_b32 s26, 0x3e0293ee
	v_readfirstlane_b32 s3, v0
	s_mul_i32 s2, s2, s3
	s_mul_hi_u32 s2, s3, s2
	s_add_i32 s3, s3, s2
	s_lshr_b32 s2, s3, 24
	s_mul_i32 s2, s2, s1
	s_sub_i32 s2, 0x100, s2
	s_sub_i32 s4, s2, s1
	s_cmp_ge_u32 s2, s1
	s_cselect_b32 s2, s4, s2
	s_sub_i32 s4, s2, s1
	s_cmp_ge_u32 s2, s1
	s_cselect_b32 s2, s4, s2
	s_sub_i32 s2, s0, s2
	s_ashr_i32 s4, s2, 31
	s_abs_i32 s2, s2
	s_mul_hi_u32 s5, s2, s3
	s_mul_i32 s5, s5, s1
	s_sub_i32 s2, s2, s5
	s_sub_i32 s5, s2, s1
	s_cmp_ge_u32 s2, s1
	s_cselect_b32 s2, s5, s2
	s_sub_i32 s5, s2, s1
	s_cmp_ge_u32 s2, s1
	s_cselect_b32 s2, s5, s2
	s_xor_b32 s2, s2, s4
	s_sub_i32 s2, s2, s4
	v_writelane_b32 v253, s2, 48
	s_cmp_lt_i32 s2, 24
	s_mul_hi_u32 s2, s3, 0x118
	s_cselect_b64 s[4:5], -1, 0
	s_mul_i32 s2, s2, s1
	v_writelane_b32 v253, s4, 49
	s_sub_i32 s2, 0x118, s2
	s_barrier
	v_writelane_b32 v253, s5, 50
	s_sub_i32 s4, s2, s1
	s_cmp_ge_u32 s2, s1
	s_cselect_b32 s2, s4, s2
	s_sub_i32 s4, s2, s1
	s_cmp_ge_u32 s2, s1
	s_cselect_b32 s2, s4, s2
	s_sub_i32 s2, s0, s2
	s_ashr_i32 s4, s2, 31
	s_abs_i32 s2, s2
	s_mul_hi_u32 s5, s2, s3
	s_mul_i32 s5, s5, s1
	s_sub_i32 s2, s2, s5
	s_sub_i32 s5, s2, s1
	s_cmp_ge_u32 s2, s1
	s_cselect_b32 s2, s5, s2
	s_sub_i32 s5, s2, s1
	s_cmp_ge_u32 s2, s1
	s_cselect_b32 s2, s5, s2
	s_xor_b32 s2, s2, s4
	s_sub_i32 s2, s2, s4
	v_writelane_b32 v253, s2, 51
	s_cmp_lt_i32 s2, 16
	s_mul_hi_u32 s2, s3, 0x128
	s_cselect_b64 s[4:5], -1, 0
	s_mul_i32 s2, s2, s1
	v_writelane_b32 v253, s4, 52
	s_sub_i32 s2, 0x128, s2
	s_nop 0
	v_writelane_b32 v253, s5, 53
	s_sub_i32 s4, s2, s1
	s_cmp_ge_u32 s2, s1
	s_cselect_b32 s2, s4, s2
	s_sub_i32 s4, s2, s1
	s_cmp_ge_u32 s2, s1
	s_cselect_b32 s2, s4, s2
	s_sub_i32 s2, s0, s2
	s_ashr_i32 s4, s2, 31
	s_abs_i32 s2, s2
	s_mul_hi_u32 s5, s2, s3
	s_mul_i32 s5, s5, s1
	s_sub_i32 s2, s2, s5
	s_sub_i32 s5, s2, s1
	s_cmp_ge_u32 s2, s1
	s_cselect_b32 s2, s5, s2
	s_sub_i32 s5, s2, s1
	s_cmp_ge_u32 s2, s1
	s_cselect_b32 s2, s5, s2
	s_xor_b32 s2, s2, s4
	s_sub_i32 s2, s2, s4
	v_writelane_b32 v253, s2, 54
	s_cmpk_lt_i32 s2, 0x80
	s_mul_hi_u32 s2, s3, 0x1a8
	s_cselect_b64 s[4:5], -1, 0
	s_mul_i32 s2, s2, s1
	v_writelane_b32 v253, s4, 55
	s_sub_i32 s2, 0x1a8, s2
	s_nop 0
	v_writelane_b32 v253, s5, 56
	s_sub_i32 s4, s2, s1
	s_cmp_ge_u32 s2, s1
	s_cselect_b32 s2, s4, s2
	s_sub_i32 s4, s2, s1
	s_cmp_ge_u32 s2, s1
	s_cselect_b32 s2, s4, s2
	s_sub_i32 s2, s0, s2
	s_ashr_i32 s4, s2, 31
	s_abs_i32 s2, s2
	s_mul_hi_u32 s5, s2, s3
	s_mul_i32 s5, s5, s1
	s_sub_i32 s2, s2, s5
	s_sub_i32 s5, s2, s1
	s_cmp_ge_u32 s2, s1
	s_cselect_b32 s2, s5, s2
	s_sub_i32 s5, s2, s1
	s_cmp_ge_u32 s2, s1
	s_cselect_b32 s2, s5, s2
	s_xor_b32 s2, s2, s4
	s_sub_i32 s2, s2, s4
	v_writelane_b32 v253, s2, 57
	s_cmp_lt_i32 s2, 64
	s_mul_hi_u32 s2, s3, 0x1e8
; DI void convert_mat(const float* W, int K, int N, const float* g, bf16_t* Wt, int mode, int& off, int vb, int nb, bool f16 = false) {
;   const int ntn = (N + 127) >> 7;
;   const int ntiles = (K >> 6) * ntn;
;   const int first = (int)((vb + nb - (off % nb)) % nb);
;   for (int i = first; i < ntiles; i += nb) convert_tile(W, K, N, g, Wt, mode, i / ntn, i % ntn, f16);
;   off += ntiles;
; }
; __global__ void __launch_bounds__(512, 2) mega(Params p) {
;     ...
;       if (L < 3) { if (odd || nb < 256) convert_layer(L + 1, bid, nb); else if (bid >= 128) convert_layer(L + 1, bid - 128, nb - 128); }
	s_cselect_b64 s[4:5], -1, 0
	s_mul_i32 s2, s2, s1
	v_writelane_b32 v253, s4, 58
	s_sub_i32 s2, 0x1e8, s2
	s_nop 0
	v_writelane_b32 v253, s5, 59
	s_sub_i32 s4, s2, s1
	s_cmp_ge_u32 s2, s1
	s_cselect_b32 s2, s4, s2
	s_sub_i32 s4, s2, s1
	s_cmp_ge_u32 s2, s1
	s_cselect_b32 s2, s4, s2
	s_sub_i32 s2, s0, s2
	s_ashr_i32 s4, s2, 31
	s_abs_i32 s2, s2
	s_mul_hi_u32 s5, s2, s3
	s_mul_i32 s5, s5, s1
	s_sub_i32 s2, s2, s5
	s_sub_i32 s5, s2, s1
	s_cmp_ge_u32 s2, s1
	s_cselect_b32 s2, s5, s2
	s_sub_i32 s5, s2, s1
	s_cmp_ge_u32 s2, s1
	s_cselect_b32 s2, s5, s2
	s_xor_b32 s2, s2, s4
	s_sub_i32 s2, s2, s4
	v_writelane_b32 v253, s2, 60
	s_cmpk_lt_i32 s2, 0x80
	s_mul_hi_u32 s2, s3, 0x268
	s_cselect_b64 s[4:5], -1, 0
	s_mul_i32 s2, s2, s1
	v_writelane_b32 v253, s4, 61
	s_sub_i32 s2, 0x268, s2
	s_nop 0
	v_writelane_b32 v253, s5, 62
	s_sub_i32 s4, s2, s1
	s_cmp_ge_u32 s2, s1
	s_cselect_b32 s2, s4, s2
	s_sub_i32 s4, s2, s1
	s_cmp_ge_u32 s2, s1
	s_cselect_b32 s2, s4, s2
	s_sub_i32 s2, s0, s2
	s_ashr_i32 s4, s2, 31
	s_abs_i32 s2, s2
	s_mul_hi_u32 s5, s2, s3
	s_mul_i32 s5, s5, s1
	s_sub_i32 s2, s2, s5
	s_sub_i32 s5, s2, s1
	s_cmp_ge_u32 s2, s1
	s_cselect_b32 s2, s5, s2
	s_sub_i32 s5, s2, s1
	s_cmp_ge_u32 s2, s1
	s_cselect_b32 s2, s5, s2
	s_xor_b32 s2, s2, s4
	s_sub_i32 s2, s2, s4
	v_writelane_b32 v253, s2, 63
	s_cmp_lt_i32 s2, 64
	s_mul_hi_u32 s2, s3, 0x2a8
	s_cselect_b64 s[4:5], -1, 0
	s_mul_i32 s2, s2, s1
	v_writelane_b32 v254, s4, 0
	s_sub_i32 s2, 0x2a8, s2
	s_nop 0
	v_writelane_b32 v254, s5, 1
	s_sub_i32 s4, s2, s1
	s_cmp_ge_u32 s2, s1
	s_cselect_b32 s2, s4, s2
	s_sub_i32 s4, s2, s1
	s_cmp_ge_u32 s2, s1
	s_cselect_b32 s2, s4, s2
	s_sub_i32 s2, s0, s2
	s_ashr_i32 s4, s2, 31
	s_abs_i32 s2, s2
	s_mul_hi_u32 s5, s2, s3
	s_mul_i32 s5, s5, s1
	s_sub_i32 s2, s2, s5
	s_sub_i32 s5, s2, s1
	s_cmp_ge_u32 s2, s1
	s_cselect_b32 s2, s5, s2
	s_sub_i32 s5, s2, s1
	s_cmp_ge_u32 s2, s1
	s_cselect_b32 s2, s5, s2
	s_xor_b32 s2, s2, s4
	s_sub_i32 s2, s2, s4
	v_writelane_b32 v254, s2, 2
	s_cmpk_lt_i32 s2, 0x2c0
	s_mul_hi_u32 s2, s3, 0x568
	s_cselect_b64 s[4:5], -1, 0
	s_mul_i32 s2, s2, s1
	v_writelane_b32 v254, s4, 3
	s_sub_i32 s2, 0x568, s2
	s_nop 0
	v_writelane_b32 v254, s5, 4
	s_sub_i32 s4, s2, s1
	s_cmp_ge_u32 s2, s1
	s_cselect_b32 s2, s4, s2
	s_sub_i32 s4, s2, s1
	s_cmp_ge_u32 s2, s1
	s_cselect_b32 s2, s4, s2
	s_sub_i32 s0, s0, s2
	s_ashr_i32 s2, s0, 31
	s_abs_i32 s0, s0
	s_mul_hi_u32 s3, s0, s3
	s_mul_i32 s3, s3, s1
	s_sub_i32 s0, s0, s3
	s_sub_i32 s3, s0, s1
	s_cmp_ge_u32 s0, s1
	s_cselect_b32 s0, s3, s0
	s_sub_i32 s3, s0, s1
	s_cmp_ge_u32 s0, s1
	s_cselect_b32 s0, s3, s0
	s_xor_b32 s0, s0, s2
	s_sub_i32 s0, s0, s2
	s_cmpk_lt_i32 s0, 0x160
	v_writelane_b32 v254, s0, 5
	s_cselect_b64 s[0:1], -1, 0
	v_writelane_b32 v254, s0, 6
	v_readlane_b32 s5, v252, 8
	v_readlane_b32 s3, v252, 9
	v_writelane_b32 v254, s1, 7
	s_lshr_b32 s0, s5, 24
	s_mul_i32 s0, s0, s3
	s_sub_i32 s0, 0x100, s0
	s_sub_i32 s1, s0, s3
	s_cmp_ge_u32 s0, s3
	s_cselect_b32 s0, s1, s0
	s_sub_i32 s1, s0, s3
	s_cmp_ge_u32 s0, s3
	s_cselect_b32 s0, s1, s0
	v_readlane_b32 s4, v252, 7
	s_sub_i32 s0, s4, s0
	s_ashr_i32 s1, s0, 31
	s_abs_i32 s0, s0
	s_mul_hi_u32 s2, s0, s5
	s_mul_i32 s2, s2, s3
	s_sub_i32 s0, s0, s2
	s_sub_i32 s2, s0, s3
	s_cmp_ge_u32 s0, s3
	s_cselect_b32 s0, s2, s0
	s_sub_i32 s2, s0, s3
	s_cmp_ge_u32 s0, s3
	s_cselect_b32 s0, s2, s0
	s_xor_b32 s0, s0, s1
	s_sub_i32 s0, s0, s1
	s_cmp_lt_i32 s0, 24
	v_writelane_b32 v254, s0, 8
	s_cselect_b64 s[0:1], -1, 0
	v_writelane_b32 v254, s0, 9
	s_nop 1
	v_writelane_b32 v254, s1, 10
	s_mul_hi_u32 s0, s5, 0x118
	s_mul_i32 s0, s0, s3
	s_sub_i32 s0, 0x118, s0
	s_sub_i32 s1, s0, s3
	s_cmp_ge_u32 s0, s3
	s_cselect_b32 s0, s1, s0
	s_sub_i32 s1, s0, s3
	s_cmp_ge_u32 s0, s3
	s_cselect_b32 s0, s1, s0
	s_sub_i32 s0, s4, s0
	s_ashr_i32 s1, s0, 31
	s_abs_i32 s0, s0
	s_mul_hi_u32 s2, s0, s5
	s_mul_i32 s2, s2, s3
	s_sub_i32 s0, s0, s2
	s_sub_i32 s2, s0, s3
	s_cmp_ge_u32 s0, s3
	s_cselect_b32 s0, s2, s0
	s_sub_i32 s2, s0, s3
	s_cmp_ge_u32 s0, s3
	s_cselect_b32 s0, s2, s0
	s_xor_b32 s0, s0, s1
	s_sub_i32 s0, s0, s1
	s_cmp_lt_i32 s0, 16
	v_writelane_b32 v254, s0, 11
	s_cselect_b64 s[0:1], -1, 0
	v_writelane_b32 v254, s0, 12
	s_nop 1
	v_writelane_b32 v254, s1, 13
	s_mul_hi_u32 s0, s5, 0x128
	s_mul_i32 s0, s0, s3
	s_sub_i32 s0, 0x128, s0
	s_sub_i32 s1, s0, s3
	s_cmp_ge_u32 s0, s3
	s_cselect_b32 s0, s1, s0
	s_sub_i32 s1, s0, s3
	s_cmp_ge_u32 s0, s3
	s_cselect_b32 s0, s1, s0
	s_sub_i32 s0, s4, s0
	s_ashr_i32 s1, s0, 31
	s_abs_i32 s0, s0
	s_mul_hi_u32 s2, s0, s5
	s_mul_i32 s2, s2, s3
	s_sub_i32 s0, s0, s2
	s_sub_i32 s2, s0, s3
	s_cmp_ge_u32 s0, s3
	s_cselect_b32 s0, s2, s0
	s_sub_i32 s2, s0, s3
	s_cmp_ge_u32 s0, s3
	s_cselect_b32 s0, s2, s0
	s_xor_b32 s0, s0, s1
	s_sub_i32 s0, s0, s1
	s_cmpk_lt_i32 s0, 0x80
	v_writelane_b32 v254, s0, 14
	s_cselect_b64 s[0:1], -1, 0
	v_writelane_b32 v254, s0, 15
	s_ashr_i32 s9, s8, 31
	s_lshl_b64 s[2:3], s[8:9], 4
	v_writelane_b32 v254, s1, 16
	s_lshl_b32 s0, s7, 2
	v_writelane_b32 v254, s0, 17
	s_lshl_b32 s0, s6, 2
	v_writelane_b32 v254, s0, 18
	s_lshl_b32 s0, s7, 8
	v_writelane_b32 v254, s0, 19
	s_lshl_b32 s0, s6, 8
	v_writelane_b32 v254, s0, 20
	s_lshl_b32 s0, s7, 1
	v_writelane_b32 v254, s0, 21
	s_lshl_b32 s0, s6, 1
	v_writelane_b32 v254, s0, 22
	s_lshl_b32 s0, s7, 5
	v_writelane_b32 v254, s0, 23
	s_lshl_b32 s0, s6, 5
	v_writelane_b32 v254, s0, 24
	s_mov_b32 s1, 0
	s_mov_b32 s0, s8
	v_writelane_b32 v254, s0, 25
	s_ashr_i32 s11, s10, 31
	s_mov_b64 s[8:9], 0
	v_writelane_b32 v254, s1, 26
	v_writelane_b32 v254, s2, 27
	s_mov_b32 s0, s10
	s_nop 0
	v_writelane_b32 v254, s3, 28
	v_writelane_b32 v254, s0, 29
	s_lshl_b64 s[2:3], s[10:11], 4
	s_mov_b64 s[10:11], 0x100
	v_writelane_b32 v254, s1, 30
	v_writelane_b32 v254, s2, 31
	s_mov_b32 s0, 0
	s_nop 0
	v_writelane_b32 v254, s3, 32
	s_mov_b64 s[2:3], -1
	v_writelane_b32 v254, s2, 33
	s_nop 1
	v_writelane_b32 v254, s3, 34
	v_writelane_b32 v254, s0, 35
	s_nop 1
	v_writelane_b32 v254, s1, 36
	v_writelane_b32 v254, s2, 37
	v_writelane_b32 v254, s3, 38
	v_writelane_b32 v254, s70, 39
	s_nop 1
	v_writelane_b32 v254, s71, 40
	s_branch .LBB0_184

; #define GSYNC() do { for (int _r = 0; _r < REP_SYNC; ++_r) xcd_barrier(xbar); } while (0)
; DI unsigned xb_ld(unsigned* p) { return __hip_atomic_load(p, __ATOMIC_RELAXED, __HIP_MEMORY_SCOPE_AGENT); }
; DI unsigned xb_add(unsigned* p, unsigned v) { return __hip_atomic_fetch_add(p, v, __ATOMIC_RELAXED, __HIP_MEMORY_SCOPE_AGENT); }
; #define XB_SPIN(cond, bar) do { unsigned _sp = 0; while (cond) { __builtin_amdgcn_s_sleep(1); \
;     if ((++_sp & 255u) == 0u) { if (xb_ld(&(bar)[XB_TMO])) break; if (_sp > XB_SPIN_CAP) { atomicAdd(&(bar)[XB_TMO], 1u); break; } } } } while (0)
; DI void xcd_barrier(const XcdBarrier& b) {
;     ...
;     if (nloc == 0u) { xcd_barrier_complete(bar, b.x, nloc, nx); b.st[0] = nloc; b.st[1] = nx; }
;     const unsigned old = xb_add(&bar[XB_XSUB(b.x)], 1u);
;     const unsigned gen = old / nloc;
;     if (old + 1u == (gen + 1u) * nloc) {
;       __builtin_amdgcn_fence(__ATOMIC_RELEASE, "agent");
;       asm volatile("s_waitcnt vmcnt(0)" ::: "memory");
;       const unsigned og = xb_add(&bar[XB_TOP], 1u);
;       const unsigned tg = og / nx;
;       if (og + 1u == (tg + 1u) * nx) xb_add(&bar[XB_TOPGEN], 1u);
;       else XB_SPIN(xb_ld(&bar[XB_TOPGEN]) == tg, bar);
;       __builtin_amdgcn_fence(__ATOMIC_ACQUIRE, "agent");
;       xb_add(&bar[XB_XGEN(b.x)], 1u);
;       asm volatile("s_waitcnt vmcnt(0)" ::: "memory");
;     } else {
;       XB_SPIN(xb_ld(&bar[XB_XGEN(b.x)]) == gen, bar);
;       __builtin_amdgcn_fence(__ATOMIC_ACQUIRE, "agent");
;       asm volatile("s_waitcnt vmcnt(0)" ::: "memory");
;     }
;   }
;   __syncthreads();
; __global__ void __launch_bounds__(512, 2) mega(Params p) {
;     ...
;     GSYNC();
;     if (odd) {
;       const int total = 3 * 64 + 8 * 64;
;       for (int rp = 0; rp < REP_P1; ++rp)
;       for (int item = bid; item < total; item += nb) {
;         if (item < 192) {
;           const int nt = item >> 6, mt = item & 63;
;           e.ss = G_SSCQ; e.nss = 4; e.inv_n = 1.f / 256.f; e.out = G_QC; e.ldo = 768;
;           gemm_tile<EPI_UQ, 256, false>(G_ZB, ZLD, wb + W_UQ, 256, mt * 256, nt * 256, e);
;         } else {
;           const int it = item - 192;
;           const int nt = it >> 6, mt = it & 63;
;           e.ss = G_SSCKV; e.nss = 2; e.inv_n = 1.f / 128.f; e.out = G_KVC; e.ldo = 1024;
;           gemm_tile<EPI_PLAIN, 128, false>(G_ZB + 256, ZLD, wb + W_UKV, 128, mt * 256, nt * 128, e);
.LBB0_542:
	s_or_b64 exec, exec, s[0:1]
	v_readlane_b32 s100, v255, 56
	s_nop 0
	s_cmp_lg_u32 s100, 2
	s_cbranch_scc1 .Lxl_known
	s_load_dwordx2 s[0:1], s[70:71], 0xc8
	v_mov_b32_e32 v0, 0x100
	s_waitcnt lgkmcnt(0)
	s_add_u32 s0, s0, 0xf8e2000
	s_addc_u32 s1, s1, 0
	global_load_dword v1, v0, s[0:1] sc1
	s_waitcnt vmcnt(0)
	v_readfirstlane_b32 s100, v1
	s_nop 0
	s_cmp_eq_u32 s100, 0
	s_cselect_b32 s100, 1, 0
	s_nop 0
	v_writelane_b32 v255, s100, 56
.Lxl_known:
	s_and_b64 vcc, exec, s[38:39]
	s_waitcnt lgkmcnt(0)
	s_barrier
	s_cbranch_vccz .LBB0_631
	v_readlane_b32 s0, v253, 34
	v_readlane_b32 s1, v253, 35
	s_andn2_b64 vcc, exec, s[0:1]
	s_cbranch_vccnz .LBB0_578
	v_readlane_b32 s0, v254, 44
	s_add_u32 s4, s0, 0x460000
	v_readlane_b32 s1, v254, 45
	s_addc_u32 s5, s1, 0
	s_add_u32 s7, s0, 0x400000
	s_addc_u32 s20, s1, 0
	v_readlane_b32 s21, v254, 17
	v_readlane_b32 s24, v254, 21
	v_readlane_b32 s25, v254, 19
	v_readlane_b32 s33, v252, 0
	s_branch .LBB0_547

; DI unsigned xb_ld(unsigned* p) { return __hip_atomic_load(p, __ATOMIC_RELAXED, __HIP_MEMORY_SCOPE_AGENT); }
; DI unsigned xb_add(unsigned* p, unsigned v) { return __hip_atomic_fetch_add(p, v, __ATOMIC_RELAXED, __HIP_MEMORY_SCOPE_AGENT); }
; #define XB_SPIN(cond, bar) do { unsigned _sp = 0; while (cond) { __builtin_amdgcn_s_sleep(1); \
;     if ((++_sp & 255u) == 0u) { if (xb_ld(&(bar)[XB_TMO])) break; if (_sp > XB_SPIN_CAP) { atomicAdd(&(bar)[XB_TMO], 1u); break; } } } } while (0)
; DI void xcd_barrier(const XcdBarrier& b) {
;     ...
;     if (old + 1u == (gen + 1u) * nloc) {
;       __builtin_amdgcn_fence(__ATOMIC_RELEASE, "agent");
;       asm volatile("s_waitcnt vmcnt(0)" ::: "memory");
;       const unsigned og = xb_add(&bar[XB_TOP], 1u);
;       const unsigned tg = og / nx;
;       if (og + 1u == (tg + 1u) * nx) xb_add(&bar[XB_TOPGEN], 1u);
;       else XB_SPIN(xb_ld(&bar[XB_TOPGEN]) == tg, bar);
;       __builtin_amdgcn_fence(__ATOMIC_ACQUIRE, "agent");
;       xb_add(&bar[XB_XGEN(b.x)], 1u);
.LBB0_977:
	s_andn2_saveexec_b64 s[2:3], s[2:3]
	s_cbranch_execz .LBB0_997
	s_mov_b64 s[2:3], exec
	v_readlane_b32 s100, v255, 56
	s_nop 0
	s_cmp_eq_u32 s100, 1
	s_cbranch_scc1 .LBB0_994
	buffer_wbl2 sc1
	s_waitcnt lgkmcnt(0)
	s_waitcnt vmcnt(0)
	v_mbcnt_lo_u32_b32 v1, s2, 0
	v_mbcnt_hi_u32_b32 v1, s3, v1
	v_cmp_eq_u32_e32 vcc, 0, v1
	s_and_saveexec_b64 s[4:5], vcc
	s_cbranch_execz .LBB0_980
	s_bcnt1_i32_b64 s2, s[2:3]
	v_mov_b32_e32 v3, s2
	v_readlane_b32 s2, v253, 23
	v_readlane_b32 s3, v253, 24
	s_nop 4
	global_atomic_add v3, v2, v3, s[2:3] sc0
